# GEMM tile head: 127 accumulator clears (v_mov_b32) -> 63 v_mov_b64 + 1 per tile in all three GEMM instances
# speedup vs baseline: 1.0062x; 1.0062x over previous
; template <class Epi>
; __device__ __forceinline__ void gemm_phase(const bf16_t* __restrict__ A, const bf16_t* __restrict__ Bt, int M, int N, LAS unsigned char* lds, const Epi& epi, int vcu) {
;     ...
;     for (int it = 0;; ++it) {
;         int nrow = brow, ncol = bcol;
;         const bool have_next = tile_rc(it + 1, nrow, ncol);
;         f32x4 acc[2][2][4][2];
; #pragma unroll
;         for (int a = 0; a < 2; ++a)
; #pragma unroll
;             for (int b = 0; b < 2; ++b)
; #pragma unroll
;                 for (int m = 0; m < 4; ++m)
; #pragma unroll
;                     for (int n = 0; n < 2; ++n) acc[a][b][m][n] = (f32x4){0.f, 0.f, 0.f, 0.f};
.LBB0_254:
	s_add_i32 s52, s42, 0x80
	s_ashr_i32 s53, s52, 31
	s_lshl_b64 s[52:53], s[52:53], 11
	s_add_u32 s52, s95, s52
	v_mov_b32_e32 v2, 0
	s_addc_u32 s53, s4, s53
	s_mov_b32 s43, -2
	s_movk_i32 s45, 0xc0
	v_mov_b32_e32 v3, v2
	v_mov_b64_e32 v[4:5], 0
	v_mov_b64_e32 v[6:7], 0
	v_mov_b64_e32 v[8:9], 0
	v_mov_b64_e32 v[18:19], 0
	v_mov_b64_e32 v[20:21], 0
	v_mov_b64_e32 v[22:23], 0
	v_mov_b64_e32 v[24:25], 0
	v_mov_b64_e32 v[34:35], 0
	v_mov_b64_e32 v[36:37], 0
	v_mov_b64_e32 v[38:39], 0
	v_mov_b64_e32 v[40:41], 0
	v_mov_b64_e32 v[50:51], 0
	v_mov_b64_e32 v[52:53], 0
	v_mov_b64_e32 v[54:55], 0
	v_mov_b64_e32 v[56:57], 0
	v_mov_b64_e32 v[10:11], 0
	v_mov_b64_e32 v[12:13], 0
	v_mov_b64_e32 v[14:15], 0
	v_mov_b64_e32 v[16:17], 0
	v_mov_b64_e32 v[26:27], 0
	v_mov_b64_e32 v[28:29], 0
	v_mov_b64_e32 v[30:31], 0
	v_mov_b64_e32 v[32:33], 0
	v_mov_b64_e32 v[42:43], 0
	v_mov_b64_e32 v[44:45], 0
	v_mov_b64_e32 v[46:47], 0
	v_mov_b64_e32 v[48:49], 0
	v_mov_b64_e32 v[58:59], 0
	v_mov_b64_e32 v[60:61], 0
	v_mov_b64_e32 v[62:63], 0
	v_mov_b64_e32 v[64:65], 0
	v_mov_b64_e32 v[66:67], 0
	v_mov_b64_e32 v[68:69], 0
	v_mov_b64_e32 v[70:71], 0
	v_mov_b64_e32 v[72:73], 0
	v_mov_b64_e32 v[82:83], 0
	v_mov_b64_e32 v[84:85], 0
	v_mov_b64_e32 v[86:87], 0
	v_mov_b64_e32 v[88:89], 0
	v_mov_b64_e32 v[98:99], 0
	v_mov_b64_e32 v[100:101], 0
	v_mov_b64_e32 v[102:103], 0
	v_mov_b64_e32 v[104:105], 0
	v_mov_b64_e32 v[114:115], 0
	v_mov_b64_e32 v[116:117], 0
	v_mov_b64_e32 v[118:119], 0
	v_mov_b64_e32 v[120:121], 0
	v_mov_b64_e32 v[74:75], 0
	v_mov_b64_e32 v[76:77], 0
	v_mov_b64_e32 v[78:79], 0
	v_mov_b64_e32 v[80:81], 0
	v_mov_b64_e32 v[90:91], 0
	v_mov_b64_e32 v[92:93], 0
	v_mov_b64_e32 v[94:95], 0
	v_mov_b64_e32 v[96:97], 0
	v_mov_b64_e32 v[106:107], 0
	v_mov_b64_e32 v[108:109], 0
	v_mov_b64_e32 v[110:111], 0
	v_mov_b64_e32 v[112:113], 0
	v_mov_b64_e32 v[122:123], 0
	v_mov_b64_e32 v[124:125], 0
	v_mov_b64_e32 v[126:127], 0
	v_mov_b64_e32 v[128:129], 0

; template <class Epi>
; __device__ __forceinline__ void gemm_phase(const bf16_t* __restrict__ A, const bf16_t* __restrict__ Bt, int M, int N, LAS unsigned char* lds, const Epi& epi, int vcu) {
;     ...
;     for (int it = 0;; ++it) {
;         int nrow = brow, ncol = bcol;
;         const bool have_next = tile_rc(it + 1, nrow, ncol);
;         f32x4 acc[2][2][4][2];
; #pragma unroll
;         for (int a = 0; a < 2; ++a)
; #pragma unroll
;             for (int b = 0; b < 2; ++b)
; #pragma unroll
;                 for (int m = 0; m < 4; ++m)
; #pragma unroll
;                     for (int n = 0; n < 2; ++n) acc[a][b][m][n] = (f32x4){0.f, 0.f, 0.f, 0.f};
.LBB0_338:
	s_add_i32 s46, s42, 0x80
	s_ashr_i32 s47, s46, 31
	s_lshl_b64 s[46:47], s[46:47], 11
	v_readlane_b32 s2, v254, 53
	s_add_u32 s46, s2, s46
	v_readlane_b32 s2, v254, 54
	v_mov_b32_e32 v2, 0
	s_addc_u32 s47, s2, s47
	s_mov_b32 s37, -2
	s_movk_i32 s43, 0xc0
	v_mov_b32_e32 v3, v2
	v_mov_b64_e32 v[4:5], 0
	v_mov_b64_e32 v[6:7], 0
	v_mov_b64_e32 v[8:9], 0
	v_mov_b64_e32 v[18:19], 0
	v_mov_b64_e32 v[20:21], 0
	v_mov_b64_e32 v[22:23], 0
	v_mov_b64_e32 v[24:25], 0
	v_mov_b64_e32 v[34:35], 0
	v_mov_b64_e32 v[36:37], 0
	v_mov_b64_e32 v[38:39], 0
	v_mov_b64_e32 v[40:41], 0
	v_mov_b64_e32 v[50:51], 0
	v_mov_b64_e32 v[52:53], 0
	v_mov_b64_e32 v[54:55], 0
	v_mov_b64_e32 v[56:57], 0
	v_mov_b64_e32 v[10:11], 0
	v_mov_b64_e32 v[12:13], 0
	v_mov_b64_e32 v[14:15], 0
	v_mov_b64_e32 v[16:17], 0
	v_mov_b64_e32 v[26:27], 0
	v_mov_b64_e32 v[28:29], 0
	v_mov_b64_e32 v[30:31], 0
	v_mov_b64_e32 v[32:33], 0
	v_mov_b64_e32 v[42:43], 0
	v_mov_b64_e32 v[44:45], 0
	v_mov_b64_e32 v[46:47], 0
	v_mov_b64_e32 v[48:49], 0
	v_mov_b64_e32 v[58:59], 0
	v_mov_b64_e32 v[60:61], 0
	v_mov_b64_e32 v[62:63], 0
	v_mov_b64_e32 v[64:65], 0
	v_mov_b64_e32 v[66:67], 0
	v_mov_b64_e32 v[68:69], 0
	v_mov_b64_e32 v[70:71], 0
	v_mov_b64_e32 v[72:73], 0
	v_mov_b64_e32 v[82:83], 0
	v_mov_b64_e32 v[84:85], 0
	v_mov_b64_e32 v[86:87], 0
	v_mov_b64_e32 v[88:89], 0
	v_mov_b64_e32 v[98:99], 0
	v_mov_b64_e32 v[100:101], 0
	v_mov_b64_e32 v[102:103], 0
	v_mov_b64_e32 v[104:105], 0
	v_mov_b64_e32 v[114:115], 0
	v_mov_b64_e32 v[116:117], 0
	v_mov_b64_e32 v[118:119], 0
	v_mov_b64_e32 v[120:121], 0
	v_mov_b64_e32 v[74:75], 0
	v_mov_b64_e32 v[76:77], 0
	v_mov_b64_e32 v[78:79], 0
	v_mov_b64_e32 v[80:81], 0
	v_mov_b64_e32 v[90:91], 0
	v_mov_b64_e32 v[92:93], 0
	v_mov_b64_e32 v[94:95], 0
	v_mov_b64_e32 v[96:97], 0
	v_mov_b64_e32 v[106:107], 0
	v_mov_b64_e32 v[108:109], 0
	v_mov_b64_e32 v[110:111], 0
	v_mov_b64_e32 v[112:113], 0
	v_mov_b64_e32 v[122:123], 0
	v_mov_b64_e32 v[124:125], 0
	v_mov_b64_e32 v[126:127], 0
	v_mov_b64_e32 v[128:129], 0

; template <class Epi>
; __device__ __forceinline__ void gemm_phase(const bf16_t* __restrict__ A, const bf16_t* __restrict__ Bt, int M, int N, LAS unsigned char* lds, const Epi& epi, int vcu) {
;     ...
;     for (int it = 0;; ++it) {
;         int nrow = brow, ncol = bcol;
;         const bool have_next = tile_rc(it + 1, nrow, ncol);
;         f32x4 acc[2][2][4][2];
; #pragma unroll
;         for (int a = 0; a < 2; ++a)
; #pragma unroll
;             for (int b = 0; b < 2; ++b)
; #pragma unroll
;                 for (int m = 0; m < 4; ++m)
; #pragma unroll
;                     for (int n = 0; n < 2; ++n) acc[a][b][m][n] = (f32x4){0.f, 0.f, 0.f, 0.f};
.LBB0_374:
	s_add_i32 s42, s14, 0x80
	s_ashr_i32 s43, s42, 31
	s_lshl_b64 s[42:43], s[42:43], 11
	v_readlane_b32 s2, v254, 53
	s_add_u32 s42, s2, s42
	v_readlane_b32 s2, v254, 54
	v_mov_b32_e32 v2, 0
	s_addc_u32 s43, s2, s43
	s_mov_b32 s15, -2
	s_movk_i32 s27, 0xc0
	v_mov_b32_e32 v3, v2
	v_mov_b64_e32 v[4:5], 0
	v_mov_b64_e32 v[6:7], 0
	v_mov_b64_e32 v[8:9], 0
	v_mov_b64_e32 v[18:19], 0
	v_mov_b64_e32 v[20:21], 0
	v_mov_b64_e32 v[22:23], 0
	v_mov_b64_e32 v[24:25], 0
	v_mov_b64_e32 v[34:35], 0
	v_mov_b64_e32 v[36:37], 0
	v_mov_b64_e32 v[38:39], 0
	v_mov_b64_e32 v[40:41], 0
	v_mov_b64_e32 v[50:51], 0
	v_mov_b64_e32 v[52:53], 0
	v_mov_b64_e32 v[54:55], 0
	v_mov_b64_e32 v[56:57], 0
	v_mov_b64_e32 v[10:11], 0
	v_mov_b64_e32 v[12:13], 0
	v_mov_b64_e32 v[14:15], 0
	v_mov_b64_e32 v[16:17], 0
	v_mov_b64_e32 v[26:27], 0
	v_mov_b64_e32 v[28:29], 0
	v_mov_b64_e32 v[30:31], 0
	v_mov_b64_e32 v[32:33], 0
	v_mov_b64_e32 v[42:43], 0
	v_mov_b64_e32 v[44:45], 0
	v_mov_b64_e32 v[46:47], 0
	v_mov_b64_e32 v[48:49], 0
	v_mov_b64_e32 v[58:59], 0
	v_mov_b64_e32 v[60:61], 0
	v_mov_b64_e32 v[62:63], 0
	v_mov_b64_e32 v[64:65], 0
	v_mov_b64_e32 v[66:67], 0
	v_mov_b64_e32 v[68:69], 0
	v_mov_b64_e32 v[70:71], 0
	v_mov_b64_e32 v[72:73], 0
	v_mov_b64_e32 v[82:83], 0
	v_mov_b64_e32 v[84:85], 0
	v_mov_b64_e32 v[86:87], 0
	v_mov_b64_e32 v[88:89], 0
	v_mov_b64_e32 v[98:99], 0
	v_mov_b64_e32 v[100:101], 0
	v_mov_b64_e32 v[102:103], 0
	v_mov_b64_e32 v[104:105], 0
	v_mov_b64_e32 v[114:115], 0
	v_mov_b64_e32 v[116:117], 0
	v_mov_b64_e32 v[118:119], 0
	v_mov_b64_e32 v[120:121], 0
	v_mov_b64_e32 v[74:75], 0
	v_mov_b64_e32 v[76:77], 0
	v_mov_b64_e32 v[78:79], 0
	v_mov_b64_e32 v[80:81], 0
	v_mov_b64_e32 v[90:91], 0
	v_mov_b64_e32 v[92:93], 0
	v_mov_b64_e32 v[94:95], 0
	v_mov_b64_e32 v[96:97], 0
	v_mov_b64_e32 v[106:107], 0
	v_mov_b64_e32 v[108:109], 0
	v_mov_b64_e32 v[110:111], 0
	v_mov_b64_e32 v[112:113], 0
	v_mov_b64_e32 v[122:123], 0
	v_mov_b64_e32 v[124:125], 0
	v_mov_b64_e32 v[126:127], 0
	v_mov_b64_e32 v[128:129], 0
